# placement flag also requires XCC ids 0-7 (block id = xcc + 8*rank must be a permutation)
# baseline (speedup 1.0000x reference)
.LBB0_16:
	v_max_u32_e32 v20, v16, v1
	v_max_u32_e32 v20, v20, v2
	v_max_u32_e32 v20, v20, v3
	v_max_u32_e32 v20, v20, v4
	v_max_u32_e32 v20, v20, v5
	v_max_u32_e32 v20, v20, v6
	v_max_u32_e32 v20, v20, v7
	v_max_u32_e32 v20, v20, v8
	v_max_u32_e32 v20, v20, v9
	v_max_u32_e32 v20, v20, v10
	v_max_u32_e32 v20, v20, v11
	v_max_u32_e32 v20, v20, v12
	v_max_u32_e32 v20, v20, v13
	v_max_u32_e32 v20, v20, v14
	v_max_u32_e32 v20, v20, v15
	v_or3_b32 v24, v8, v9, v10
	v_or3_b32 v24, v24, v11, v12
	v_or3_b32 v24, v24, v13, v14
	v_or_b32_e32 v24, v24, v15
	v_readlane_b32 s6, v243, 2
	s_cmp_eq_u32 s6, 0
	s_cselect_b64 vcc, -1, 0
	s_cmp_eq_u32 s6, 1
	v_cndmask_b32_e32 v17, 0, v16, vcc
	s_cselect_b64 vcc, -1, 0
	s_cmp_eq_u32 s6, 2
	v_cndmask_b32_e32 v17, v17, v1, vcc
	s_cselect_b64 vcc, -1, 0
	s_cmp_eq_u32 s6, 3
	v_cndmask_b32_e32 v17, v17, v2, vcc
	s_cselect_b64 vcc, -1, 0
	s_cmp_eq_u32 s6, 4
	v_cndmask_b32_e32 v17, v17, v3, vcc
	s_cselect_b64 vcc, -1, 0
	s_cmp_eq_u32 s6, 5
	v_cndmask_b32_e32 v17, v17, v4, vcc
	s_cselect_b64 vcc, -1, 0
	s_cmp_eq_u32 s6, 6
	v_cndmask_b32_e32 v17, v17, v5, vcc
	s_cselect_b64 vcc, -1, 0
	s_cmp_eq_u32 s6, 7
	v_cndmask_b32_e32 v17, v17, v6, vcc
	s_cselect_b64 vcc, -1, 0
	s_cmp_eq_u32 s6, 8
	v_cndmask_b32_e32 v17, v17, v7, vcc
	s_cselect_b64 vcc, -1, 0
	s_cmp_eq_u32 s6, 9
	v_cndmask_b32_e32 v17, v17, v8, vcc
	s_cselect_b64 vcc, -1, 0
	s_cmp_eq_u32 s6, 10
	v_cndmask_b32_e32 v17, v17, v9, vcc
	s_cselect_b64 vcc, -1, 0
	s_cmp_eq_u32 s6, 11
	v_cndmask_b32_e32 v17, v17, v10, vcc
	s_cselect_b64 vcc, -1, 0
	s_cmp_eq_u32 s6, 12
	v_cndmask_b32_e32 v17, v17, v11, vcc
	s_cselect_b64 vcc, -1, 0
	s_cmp_eq_u32 s6, 13
	v_cndmask_b32_e32 v17, v17, v12, vcc
	s_cselect_b64 vcc, -1, 0
	s_cmp_eq_u32 s6, 14
	v_cndmask_b32_e32 v17, v17, v13, vcc
	s_cselect_b64 vcc, -1, 0
	s_cmp_eq_u32 s6, 15
	v_cndmask_b32_e32 v17, v17, v14, vcc
	s_cselect_b64 vcc, -1, 0
	v_cndmask_b32_e32 v17, v17, v15, vcc
	v_cmp_ne_u32_e32 vcc, 0, v16
	s_nop 1
	v_cndmask_b32_e64 v16, 0, 1, vcc
	v_cmp_ne_u32_e32 vcc, 0, v1
	s_nop 1
	v_addc_co_u32_e32 v1, vcc, 0, v16, vcc
	v_cmp_ne_u32_e32 vcc, 0, v2
	s_nop 1
	v_cndmask_b32_e64 v2, 0, 1, vcc
	v_cmp_ne_u32_e32 vcc, 0, v3
	v_mov_b32_e32 v3, 0
	s_nop 0
	v_addc_co_u32_e32 v1, vcc, v1, v2, vcc
	v_cmp_ne_u32_e32 vcc, 0, v4
	s_nop 1
	v_cndmask_b32_e64 v2, 0, 1, vcc
	v_cmp_ne_u32_e32 vcc, 0, v5
	s_nop 1
	v_addc_co_u32_e32 v1, vcc, v1, v2, vcc
	v_cmp_ne_u32_e32 vcc, 0, v6
	s_nop 1
	v_cndmask_b32_e64 v2, 0, 1, vcc
	v_cmp_ne_u32_e32 vcc, 0, v7
	s_nop 1
	v_addc_co_u32_e32 v1, vcc, v1, v2, vcc
	v_cmp_ne_u32_e32 vcc, 0, v8
	s_nop 1
	v_cndmask_b32_e64 v2, 0, 1, vcc
	v_cmp_ne_u32_e32 vcc, 0, v9
	s_nop 1
	v_addc_co_u32_e32 v1, vcc, v1, v2, vcc
	v_cmp_ne_u32_e32 vcc, 0, v10
	s_nop 1
	v_cndmask_b32_e64 v2, 0, 1, vcc
	v_cmp_ne_u32_e32 vcc, 0, v11
	s_nop 1
	v_addc_co_u32_e32 v1, vcc, v1, v2, vcc
	v_cmp_ne_u32_e32 vcc, 0, v12
	s_nop 1
	v_cndmask_b32_e64 v2, 0, 1, vcc
	v_cmp_ne_u32_e32 vcc, 0, v13
	s_nop 1
	v_addc_co_u32_e32 v1, vcc, v1, v2, vcc
	v_cmp_ne_u32_e32 vcc, 0, v14
	s_nop 1
	v_cndmask_b32_e64 v2, 0, 1, vcc
	v_cmp_ne_u32_e32 vcc, 0, v15
	s_nop 1
	v_addc_co_u32_e32 v1, vcc, v1, v2, vcc
	v_max_u32_e32 v2, 1, v17
	v_max_u32_e32 v1, 1, v1
	ds_write_b32 v3, v2
	ds_write_b32 v3, v1 offset:4
	v_cmp_eq_u32_e32 vcc, 32, v20
	s_nop 1
	v_cndmask_b32_e64 v21, 0, 1, vcc
	v_cmp_eq_u32_e32 vcc, 8, v1
	s_nop 1
	v_cndmask_b32_e64 v22, 0, 1, vcc
	v_and_b32_e32 v21, v21, v22
	v_cmp_eq_u32_e32 vcc, 0, v24
	s_nop 1
	v_cndmask_b32_e64 v22, 0, 1, vcc
	v_and_b32_e32 v21, v21, v22
	v_lshl_add_u32 v22, v19, 3, s6
	v_mov_b32_e32 v23, s33
	v_cmp_ne_u32_e32 vcc, 0, v21
	s_nop 1
	v_cndmask_b32_e32 v22, v23, v22, vcc
	ds_write_b32 v3, v22 offset:8
	ds_write_b32 v3, v21 offset:12
